# conv work moved off the two carry-scan waves (waves 2-7 stride 384); phase-H fold_partials slice loads issued 4 at a time
# speedup vs baseline: 1.0113x; 1.0113x over previous
; __device__ __forceinline__ int tid_() { int t = threadIdx.x; asm volatile("" : "+v"(t)); return t; }
; __device__ __forceinline__ int bid_() { int t = blockIdx.x; asm volatile("" : "+s"(t)); return t; }
; __device__ __forceinline__ int nblk_() { int t = gridDim.x; asm volatile("" : "+s"(t)); return t; }
; __device__ __forceinline__ void carry_scan(KArgs& a, int l) {
;     ...
;     if (nblk_() * 128 >= 8 * 32 * 2 * 64) { if (tid_() >= 128) return; gt = bid_() * 128 + tid_(); } else gt = bid_() * 512 + tid_();
;     if (gt >= 8 * 32 * 2 * 64) return;
; __device__ __forceinline__ void conv_all(KArgs& a, int l) {
;     const size_t gt = (size_t)bid_() * 512 + tid_(), gn = (size_t)nblk_() * 512;
;     const bf16_t* PA = (const bf16_t*)(a.ws + OFF_R1); bf16_t* AC = (bf16_t*)(a.ws + OFF_R2);
;     const float* cw = a.conv_w + l * 3 * 512;
;     for (size_t e = gt; e < (size_t)MTOK * 64; e += gn) {
;         const int r = (int)(e >> 6), c0 = (int)(e & 63) * 8; const int t = r % TPB;
;         const bf16_t* pr = PA + (size_t)r * PALD + c0;
;         float xa[8], xb[8], xc[8], vm[8], vp[8];
;         unpack8(*(const u32x4*)pr, xa); unpack8(*(const u32x4*)(pr + 512), xb); unpack8(*(const u32x4*)(pr + 1024), xc);
;         const bool hasm = (t != 0 && t != CTXL), hasp = (t != CTXL - 1 && t != TPB - 1);
;         if (hasm) { float q1[8], q2[8]; unpack8(*(const u32x4*)(pr - PALD), q1); unpack8(*(const u32x4*)(pr - PALD + 1024), q2);
; #pragma unroll
;             for (int i = 0; i < 8; ++i) vm[i] = q1[i] * q2[i]; }
;         else {
; #pragma unroll
;             for (int i = 0; i < 8; ++i) vm[i] = 0.f; }
;         if (hasp) { float q1[8], q2[8]; unpack8(*(const u32x4*)(pr + PALD), q1); unpack8(*(const u32x4*)(pr + PALD + 1024), q2);
; #pragma unroll
;             for (int i = 0; i < 8; ++i) vp[i] = q1[i] * q2[i]; }
;         else {
; #pragma unroll
;             for (int i = 0; i < 8; ++i) vp[i] = 0.f; }
;         float o[8];
; #pragma unroll
;         for (int i = 0; i < 8; ++i) o[i] = xb[i] * (cw[c0 + i] * vm[i] + cw[512 + c0 + i] * (xa[i] * xc[i]) + cw[1024 + c0 + i] * vp[i]);
;         u32x4 ov; ov.x = pk2(o[0], o[1]); ov.y = pk2(o[2], o[3]); ov.z = pk2(o[4], o[5]); ov.w = pk2(o[6], o[7]);
;         *(u32x4*)(AC + (size_t)r * 512 + c0) = ov;
;     }
.LBB0_604:
	s_or_b64 exec, exec, s[22:23]
	s_mov_b32 s22, s84
	s_ashr_i32 s23, s22, 31
	v_mov_b32_e32 v2, v216
	s_lshl_b64 s[0:1], s[22:23], 9
	s_nop 0
	v_ashrrev_i32_e32 v3, 31, v2
	v_lshl_add_u64 v[14:15], s[0:1], 0, v[2:3]
	v_readlane_b32 s0, v237, 2
	v_readlane_b32 s1, v237, 3
	s_load_dwordx2 s[24:25], s[0:1], 0xf0
	s_mov_b64 s[0:1], 0x220000
	v_cmp_gt_u64_e32 vcc, s[0:1], v[14:15]
	s_waitcnt lgkmcnt(0)
	s_and_saveexec_b64 s[0:1], vcc
	s_cbranch_execz .LBB0_611
	s_ashr_i32 s25, s24, 31
	s_lshl_b64 s[8:9], s[24:25], 9
	s_load_dwordx2 s[2:3], s[14:15], 0x40
	s_add_u32 s14, s16, 0xcaf8000
	s_addc_u32 s15, s17, 0
	s_add_u32 s16, s16, 0x196f8000
	s_mulk_i32 s4, 0x600
	s_addc_u32 s17, s17, 0
	s_ashr_i32 s5, s4, 31
	s_lshl_b64 s[4:5], s[4:5], 2
	s_waitcnt lgkmcnt(0)
	s_add_u32 s4, s2, s4
	s_addc_u32 s5, s3, s5
	s_lshl_b64 s[2:3], s[22:23], 12
	v_lshl_add_u64 v[16:17], v[2:3], 3, s[2:3]
	s_lshl_b64 s[22:23], s[24:25], 12
	s_mov_b64 s[24:25], 0
	v_readfirstlane_b32 s2, v216
	s_nop 3
	s_cmp_lt_u32 s2, 0x80
	s_cbranch_scc1 .Lconv_done
	v_readlane_b32 s3, v236, 25
	s_nop 3
	s_mul_i32 s3, s3, 0x180
	s_sub_i32 s3, s3, 0x80
	v_add_u32_e32 v14, s3, v216
	v_mov_b32_e32 v15, v1
	v_lshlrev_b32_e32 v16, 3, v14
	v_mov_b32_e32 v17, v1
	s_lshr_b64 s[2:3], s[8:9], 2
	s_sub_u32 s8, s8, s2
	s_subb_u32 s9, s9, s3
	s_lshr_b64 s[2:3], s[22:23], 2
	s_sub_u32 s22, s22, s2
	s_subb_u32 s23, s23, s3
	v_and_b32_e32 v38, 0x1f8, v16
	v_lshlrev_b32_e32 v36, 2, v38
	v_lshlrev_b32_e32 v0, 1, v38
	v_mov_b32_e32 v37, v1
	global_load_dwordx4 v[148:151], v36, s[4:5]
	global_load_dwordx4 v[152:155], v36, s[4:5] offset:16
	global_load_dwordx4 v[156:159], v36, s[4:5] offset:2048
	global_load_dwordx4 v[160:163], v36, s[4:5] offset:2064
	v_lshl_add_u64 v[44:45], s[4:5], 0, v[36:37]
	s_mov_b64 s[2:3], 0x1000
	v_lshl_add_u64 v[44:45], v[44:45], 0, s[2:3]
	global_load_dwordx4 v[164:167], v[44:45], off
	global_load_dwordx4 v[168:171], v[44:45], off offset:16
	v_lshrrev_b64 v[18:19], 6, v[14:15]
	v_lshlrev_b64 v[2:3], 12, v[18:19]
	v_lshl_add_u64 v[2:3], s[14:15], 0, v[2:3]
	v_lshl_add_u64 v[172:173], v[2:3], 0, v[0:1]
	global_load_dwordx4 v[176:179], v[172:173], off
	global_load_dwordx4 v[180:183], v[172:173], off offset:1024
	global_load_dwordx4 v[184:187], v[172:173], off offset:2048
	global_load_dwordx4 v[188:191], v[172:173], off offset:-4096
	global_load_dwordx4 v[192:195], v[172:173], off offset:-2048
	v_lshl_add_u64 v[2:3], v[172:173], 0, s[2:3]
	global_load_dwordx4 v[196:199], v[2:3], off
	global_load_dwordx4 v[200:203], v[2:3], off offset:2048
	s_waitcnt vmcnt(0)

; #define LAS __attribute__((address_space(3)))
; __device__ __forceinline__ bool fold_partials(f32x4 (&v)[4], const LAS unsigned char* tmap, const float* PB, int r, int lane) {
;     const int pm = r >> 8, rl = r & 255; bool any = false;
; #pragma unroll
;     for (int j = 0; j < 4; ++j) { const int q = tmap[pm * 4 + j];
;         if (q != 0xff) { any = true;
; #pragma unroll
;             for (int sl = 0; sl < 4; ++sl) v[j] += *(const f32x4*)(PB + ((size_t)(sl * 32 + q) * 256 + rl) * 256 + lane * 4); } }
;     return any;
; }
; __device__ __forceinline__ void prenorm_row(float* xr, const float* g, const float* shift, const float* scale, bf16_t* orow, int lane, const LAS unsigned char* tmap, const float* PB, int r) {
;     f32x4 v[4]; float s = 0.f;
; #pragma unroll
;     for (int j = 0; j < 4; ++j) v[j] = ((const f32x4*)xr)[lane + 64 * j];
;     if (PB) { if (fold_partials(v, tmap, PB, r, lane)) {
; __device__ __forceinline__ void prenorm_all(KArgs& a, LAS unsigned char* lds, const float* g, const float* mods_l, int si, bf16_t* Hn, const float* PB) {
;     ...
;     for (int r = gw; r < MTOK; r += ngw) {
;         const int b = r / TPB, t = r - b * TPB; const float* md = mods_l + (size_t)(t < CTXL ? 8 : b) * 6144;
;         prenorm_row(xrow(a, r), g, md + si * DM, md + (si + 1) * DM, Hn + (size_t)r * DM, lane, tmap, PB, r);
.LBB0_1132:
	v_mul_hi_i32 v0, v50, s89
	v_lshrrev_b32_e32 v2, 31, v0
	v_ashrrev_i32_e32 v0, 11, v0
	v_add_u32_e32 v66, v0, v2
	s_movk_i32 s0, 0xef00
	v_mad_i32_i24 v0, v66, s0, v50
	v_add_u32_e32 v4, 0xffffff00, v0
	v_mov_b32_e32 v2, s53
	v_mov_b32_e32 v3, s55
	v_cmp_gt_i32_e64 s[40:41], s96, v0
	v_ashrrev_i32_e32 v67, 31, v66
	v_ashrrev_i32_e32 v5, 31, v0
	v_cndmask_b32_e64 v3, v2, v3, s[40:41]
	v_mov_b32_e32 v2, s52
	v_mov_b32_e32 v6, s54
	v_cndmask_b32_e64 v4, v4, v0, s[40:41]
	v_cndmask_b32_e64 v0, 24, 20, s[40:41]
	v_cndmask_b32_e64 v2, v2, v6, s[40:41]
	v_cndmask_b32_e64 v5, 0, v5, s[40:41]
	v_lshlrev_b64 v[6:7], v0, v[66:67]
	v_lshl_add_u64 v[2:3], v[2:3], 0, v[6:7]
	v_lshlrev_b64 v[4:5], 12, v[4:5]
	v_lshl_add_u64 v[2:3], v[2:3], 0, v[4:5]
	v_lshlrev_b32_e32 v0, 4, v52
	v_lshl_add_u64 v[68:69], v[2:3], 0, v[0:1]
	global_load_dwordx4 v[18:21], v[68:69], off
	global_load_dwordx4 v[22:25], v[68:69], off offset:1024
	global_load_dwordx4 v[26:29], v[68:69], off offset:2048
	global_load_dwordx4 v[30:33], v[68:69], off offset:3072
	s_and_b64 vcc, exec, s[4:5]
	s_cbranch_vccz .LBB0_1144
	v_ashrrev_i32_e32 v2, 6, v50
	v_and_b32_e32 v2, -4, v2
	v_add_u32_e32 v3, 0, v2
	v_add_u32_e32 v3, 0x222e0, v3
	ds_read_u8 v3, v3
	v_and_b32_e32 v4, 0xff00, v75
	s_waitcnt vmcnt(0)
	v_mov_b32_e32 v34, v18
	v_mov_b32_e32 v35, v19
	v_lshlrev_b32_e32 v51, 2, v4
	s_waitcnt lgkmcnt(0)
	v_cmp_ne_u16_e64 s[0:1], s90, v3
	v_mov_b32_e32 v36, v20
	v_mov_b32_e32 v37, v21
	v_mov_b32_e32 v38, v22
	v_mov_b32_e32 v39, v23
	v_mov_b32_e32 v40, v24
	v_mov_b32_e32 v41, v25
	v_mov_b32_e32 v42, v26
	v_mov_b32_e32 v43, v27
	v_mov_b32_e32 v44, v28
	v_mov_b32_e32 v45, v29
	v_mov_b32_e32 v46, v30
	v_mov_b32_e32 v47, v31
	v_mov_b32_e32 v48, v32
	v_mov_b32_e32 v49, v33
	s_and_saveexec_b64 s[8:9], s[0:1]
	s_cbranch_execz .LBB0_1135
	v_lshl_or_b32 v4, v3, 18, v51
	v_mov_b32_e32 v5, v1
	v_lshl_add_u64 v[8:9], v[54:55], 0, v[4:5]
	global_load_dwordx4 v[4:7], v[8:9], off
	v_add_co_u32_e32 v190, vcc, 0x800000, v8
	s_nop 1
	v_addc_co_u32_e32 v191, vcc, 0, v9, vcc
	global_load_dwordx4 v[192:195], v[190:191], off
	v_add_co_u32_e32 v190, vcc, 0x1000000, v8
	s_nop 1
	v_addc_co_u32_e32 v191, vcc, 0, v9, vcc
	global_load_dwordx4 v[196:199], v[190:191], off
	v_add_co_u32_e32 v190, vcc, 0x1800000, v8
	s_nop 1
	v_addc_co_u32_e32 v191, vcc, 0, v9, vcc
	global_load_dwordx4 v[200:203], v[190:191], off
	v_mov_b32_e32 v38, v22
	v_mov_b32_e32 v39, v23
	v_mov_b32_e32 v40, v24
	v_mov_b32_e32 v41, v25
	v_mov_b32_e32 v42, v26
	v_mov_b32_e32 v43, v27
	v_mov_b32_e32 v44, v28
	v_mov_b32_e32 v45, v29
	v_mov_b32_e32 v46, v30
	v_mov_b32_e32 v47, v31
	v_mov_b32_e32 v48, v32
	v_mov_b32_e32 v49, v33
	s_waitcnt vmcnt(3)
	v_pk_add_f32 v[12:13], v[18:19], v[4:5]
	v_pk_add_f32 v[10:11], v[20:21], v[6:7]
	s_nop 0
	s_waitcnt vmcnt(2)
	v_pk_add_f32 v[12:13], v[192:193], v[12:13]
	v_pk_add_f32 v[10:11], v[194:195], v[10:11]
	s_nop 0
	s_waitcnt vmcnt(1)
	v_pk_add_f32 v[12:13], v[196:197], v[12:13]
	v_pk_add_f32 v[10:11], v[198:199], v[10:11]
	s_nop 0
	s_waitcnt vmcnt(0)
	v_pk_add_f32 v[36:37], v[202:203], v[10:11]
	v_pk_add_f32 v[34:35], v[200:201], v[12:13]
; #define LAS __attribute__((address_space(3)))
; __device__ __forceinline__ bool fold_partials(f32x4 (&v)[4], const LAS unsigned char* tmap, const float* PB, int r, int lane) {
;     const int pm = r >> 8, rl = r & 255; bool any = false;
; #pragma unroll
;     for (int j = 0; j < 4; ++j) { const int q = tmap[pm * 4 + j];
;         if (q != 0xff) { any = true;
; #pragma unroll
;             for (int sl = 0; sl < 4; ++sl) v[j] += *(const f32x4*)(PB + ((size_t)(sl * 32 + q) * 256 + rl) * 256 + lane * 4); } }
;     return any;
.LBB0_1135:
	s_or_b64 exec, exec, s[8:9]
	v_readlane_b32 s3, v236, 18
	s_nop 1
	v_add_u32_e32 v61, s3, v2
	ds_read_u8 v63, v61 offset:1
	v_mov_b64_e32 v[2:3], v[34:35]
	v_mov_b64_e32 v[4:5], v[36:37]
	v_mov_b64_e32 v[6:7], v[38:39]
	v_mov_b64_e32 v[8:9], v[40:41]
	s_waitcnt lgkmcnt(0)
	v_cmp_ne_u16_e32 vcc, s90, v63
	v_mov_b64_e32 v[10:11], v[42:43]
	v_mov_b64_e32 v[12:13], v[44:45]
	v_mov_b64_e32 v[14:15], v[46:47]
	v_mov_b64_e32 v[16:17], v[48:49]
	s_and_saveexec_b64 s[8:9], vcc
	s_cbranch_execz .LBB0_1137
	v_lshl_or_b32 v2, v63, 18, v51
	v_mov_b32_e32 v3, v1
	v_lshl_add_u64 v[6:7], v[54:55], 0, v[2:3]
	global_load_dwordx4 v[2:5], v[6:7], off
	v_add_co_u32_e32 v190, vcc, 0x800000, v6
	s_nop 1
	v_addc_co_u32_e32 v191, vcc, 0, v7, vcc
	global_load_dwordx4 v[192:195], v[190:191], off
	v_add_co_u32_e32 v190, vcc, 0x1000000, v6
	s_nop 1
	v_addc_co_u32_e32 v191, vcc, 0, v7, vcc
	global_load_dwordx4 v[196:199], v[190:191], off
	v_add_co_u32_e32 v190, vcc, 0x1800000, v6
	s_nop 1
	v_addc_co_u32_e32 v191, vcc, 0, v7, vcc
	global_load_dwordx4 v[200:203], v[190:191], off
	s_or_b64 s[0:1], s[0:1], exec
	s_waitcnt vmcnt(3)
	v_pk_add_f32 v[10:11], v[38:39], v[2:3]
	v_pk_add_f32 v[8:9], v[40:41], v[4:5]
	s_nop 0
	s_waitcnt vmcnt(2)
	v_pk_add_f32 v[10:11], v[192:193], v[10:11]
	v_pk_add_f32 v[8:9], v[194:195], v[8:9]
	s_nop 0
	s_waitcnt vmcnt(1)
	v_pk_add_f32 v[10:11], v[196:197], v[10:11]
	v_pk_add_f32 v[8:9], v[198:199], v[8:9]
	s_nop 0
	s_waitcnt vmcnt(0)
	v_pk_add_f32 v[40:41], v[202:203], v[8:9]
	v_pk_add_f32 v[38:39], v[200:201], v[10:11]
	s_nop 0
	v_mov_b64_e32 v[2:3], v[34:35]
	v_mov_b64_e32 v[4:5], v[36:37]
	v_mov_b64_e32 v[6:7], v[38:39]
	v_mov_b64_e32 v[8:9], v[40:41]
	v_mov_b64_e32 v[10:11], v[42:43]
	v_mov_b64_e32 v[12:13], v[44:45]
	v_mov_b64_e32 v[14:15], v[46:47]
	v_mov_b64_e32 v[16:17], v[48:49]
.LBB0_1137:
	s_or_b64 exec, exec, s[8:9]
	ds_read_u8 v63, v61 offset:2
	s_waitcnt lgkmcnt(0)
	v_cmp_ne_u16_e32 vcc, s90, v63
	s_and_saveexec_b64 s[8:9], vcc
	s_cbranch_execz .LBB0_1139
	v_lshl_or_b32 v2, v63, 18, v51
	v_mov_b32_e32 v3, v1
	v_lshl_add_u64 v[6:7], v[54:55], 0, v[2:3]
	global_load_dwordx4 v[2:5], v[6:7], off
	v_add_co_u32_e32 v190, vcc, 0x800000, v6
	s_nop 1
	v_addc_co_u32_e32 v191, vcc, 0, v7, vcc
	global_load_dwordx4 v[192:195], v[190:191], off
	v_add_co_u32_e32 v190, vcc, 0x1000000, v6
	s_nop 1
	v_addc_co_u32_e32 v191, vcc, 0, v7, vcc
	global_load_dwordx4 v[196:199], v[190:191], off
	v_add_co_u32_e32 v190, vcc, 0x1800000, v6
	s_nop 1
	v_addc_co_u32_e32 v191, vcc, 0, v7, vcc
	global_load_dwordx4 v[200:203], v[190:191], off
	s_or_b64 s[0:1], s[0:1], exec
	s_waitcnt vmcnt(3)
	v_pk_add_f32 v[10:11], v[10:11], v[2:3]
	v_pk_add_f32 v[8:9], v[12:13], v[4:5]
	s_nop 0
	s_waitcnt vmcnt(2)
	v_pk_add_f32 v[10:11], v[192:193], v[10:11]
	v_pk_add_f32 v[8:9], v[194:195], v[8:9]
	s_nop 0
	s_waitcnt vmcnt(1)
	v_pk_add_f32 v[10:11], v[196:197], v[10:11]
	v_pk_add_f32 v[8:9], v[198:199], v[8:9]
	s_nop 0
	s_waitcnt vmcnt(0)
	v_pk_add_f32 v[44:45], v[202:203], v[8:9]
	v_pk_add_f32 v[42:43], v[200:201], v[10:11]
	s_nop 0
	v_mov_b64_e32 v[2:3], v[34:35]
	v_mov_b64_e32 v[4:5], v[36:37]
	v_mov_b64_e32 v[6:7], v[38:39]
	v_mov_b64_e32 v[8:9], v[40:41]
	v_mov_b64_e32 v[10:11], v[42:43]
	v_mov_b64_e32 v[12:13], v[44:45]
	v_mov_b64_e32 v[14:15], v[46:47]
	v_mov_b64_e32 v[16:17], v[48:49]
.LBB0_1139:
	s_or_b64 exec, exec, s[8:9]
	ds_read_u8 v61, v61 offset:3
	s_waitcnt lgkmcnt(0)
	v_cmp_ne_u16_e32 vcc, s90, v61
	s_and_saveexec_b64 s[8:9], vcc
	s_cbranch_execz .LBB0_1141
	v_lshl_or_b32 v2, v61, 18, v51
	v_mov_b32_e32 v3, v1
	v_lshl_add_u64 v[6:7], v[54:55], 0, v[2:3]
	global_load_dwordx4 v[2:5], v[6:7], off
	v_add_co_u32_e32 v190, vcc, 0x800000, v6
	s_nop 1
	v_addc_co_u32_e32 v191, vcc, 0, v7, vcc
	global_load_dwordx4 v[192:195], v[190:191], off
	v_add_co_u32_e32 v190, vcc, 0x1000000, v6
	s_nop 1
	v_addc_co_u32_e32 v191, vcc, 0, v7, vcc
	global_load_dwordx4 v[196:199], v[190:191], off
	v_add_co_u32_e32 v190, vcc, 0x1800000, v6
	s_nop 1
	v_addc_co_u32_e32 v191, vcc, 0, v7, vcc
	global_load_dwordx4 v[200:203], v[190:191], off
	s_or_b64 s[0:1], s[0:1], exec
	s_waitcnt vmcnt(3)
	v_pk_add_f32 v[10:11], v[14:15], v[2:3]
	v_pk_add_f32 v[8:9], v[16:17], v[4:5]
	s_nop 0
	s_waitcnt vmcnt(2)
	v_pk_add_f32 v[10:11], v[192:193], v[10:11]
	v_pk_add_f32 v[8:9], v[194:195], v[8:9]
	s_nop 0
	s_waitcnt vmcnt(1)
	v_pk_add_f32 v[10:11], v[196:197], v[10:11]
	v_pk_add_f32 v[8:9], v[198:199], v[8:9]
	s_nop 0
	s_waitcnt vmcnt(0)
	v_pk_add_f32 v[48:49], v[202:203], v[8:9]
	v_pk_add_f32 v[46:47], v[200:201], v[10:11]
	s_nop 0
	v_mov_b64_e32 v[2:3], v[34:35]
	v_mov_b64_e32 v[4:5], v[36:37]
	v_mov_b64_e32 v[6:7], v[38:39]
	v_mov_b64_e32 v[8:9], v[40:41]
	v_mov_b64_e32 v[10:11], v[42:43]
	v_mov_b64_e32 v[12:13], v[44:45]
	v_mov_b64_e32 v[14:15], v[46:47]
	v_mov_b64_e32 v[16:17], v[48:49]
